# y read-back issued behind the last step of the chunk
# speedup vs baseline: 1.0044x; 1.0044x over previous
.LBB0_682:
	s_bitcmp1_b32 s30, 0
	s_cselect_b32 s6, 0xe000, 0
	s_add_i32 s6, s6, 0
	v_add_u32_e32 v90, s6, v58
	v_sub_u32_e32 v88, v90, v61
	v_add_u32_e32 v89, s6, v86
	ds_read_b128 v[4:7], v90 offset:0x4000
	ds_read_b128 v[8:11], v90 offset:0x0
	ds_read2st64_b32 v[108:109], v89 offset0:192 offset1:193
	ds_read2st64_b64 v[100:103], v88 offset0:64 offset1:65
	ds_read_b128 v[112:115], v90 offset:0x4200
	ds_read_b128 v[96:99], v90 offset:0x200
	v_mov_b32_e32 v93, v91
	s_waitcnt lgkmcnt(3)
	v_pk_mul_f32 v[0:1], v[52:53], v[4:5] op_sel_hi:[0,1]
	v_pk_fma_f32 v[0:1], v[52:53], v[6:7], v[0:1] op_sel:[1,0,0]
	v_pk_mul_f32 v[10:11], v[108:109], v[10:11] op_sel_hi:[0,1]
	ds_read_b128 v[4:7], v90 offset:0x4400
	v_add_f32_dpp v0, v0, v0 quad_perm:[1,0,3,2] row_mask:0xf bank_mask:0xf bound_ctrl:1
	v_add_f32_dpp v1, v1, v1 quad_perm:[1,0,3,2] row_mask:0xf bank_mask:0xf bound_ctrl:1
	v_pk_fma_f32 v[54:55], v[52:53], v[8:9], v[10:11]
	v_add_f32_dpp v0, v0, v0 quad_perm:[2,3,0,1] row_mask:0xf bank_mask:0xf bound_ctrl:1
	ds_read_b128 v[8:11], v90 offset:0x400
	s_nop 0
	v_add_f32_dpp v0, v0, v0 row_half_mirror row_mask:0xf bank_mask:0xf bound_ctrl:1
	s_nop 0
	s_nop 0
	v_add_f32_dpp v2, v0, v0 row_mirror row_mask:0xf bank_mask:0xf bound_ctrl:1
	v_add_f32_dpp v0, v0, v0 row_mirror row_mask:0xf bank_mask:0xf bound_ctrl:1
	ds_read2st64_b32 v[110:111], v89 offset0:194 offset1:195
	s_waitcnt lgkmcnt(3)
	v_permlane16_swap_b32_e32 v0, v2
	v_add_f32_e32 v0, v0, v2
	v_pk_fma_f32 v[52:53], v[100:101], v[0:1], v[54:55] op_sel_hi:[1,0,1]
	v_pk_mul_f32 v[118:119], v[52:53], v[112:113] op_sel_hi:[0,1]
	v_pk_fma_f32 v[118:119], v[52:53], v[114:115], v[118:119] op_sel:[1,0,0]
	v_pk_mul_f32 v[98:99], v[108:109], v[98:99] op_sel:[1,0]
	ds_read_b128 v[112:115], v90 offset:0x4600
	v_add_f32_dpp v118, v118, v118 quad_perm:[1,0,3,2] row_mask:0xf bank_mask:0xf bound_ctrl:1
	v_add_f32_dpp v119, v119, v119 quad_perm:[1,0,3,2] row_mask:0xf bank_mask:0xf bound_ctrl:1
	v_pk_fma_f32 v[54:55], v[52:53], v[96:97], v[98:99]
	v_add_f32_dpp v118, v118, v118 quad_perm:[2,3,0,1] row_mask:0xf bank_mask:0xf bound_ctrl:1
	ds_read_b128 v[96:99], v90 offset:0x600
	s_nop 0
	v_add_f32_dpp v118, v118, v118 row_half_mirror row_mask:0xf bank_mask:0xf bound_ctrl:1
	ds_write2_b32 v93, v1, v119 offset0:0 offset1:36
	s_nop 0
	v_add_f32_dpp v2, v118, v118 row_mirror row_mask:0xf bank_mask:0xf bound_ctrl:1
	v_add_f32_dpp v118, v118, v118 row_mirror row_mask:0xf bank_mask:0xf bound_ctrl:1
	ds_read2st64_b64 v[104:107], v88 offset0:66 offset1:67
	s_waitcnt lgkmcnt(4)
	v_permlane16_swap_b32_e32 v118, v2
	v_add_f32_e32 v118, v118, v2
	v_pk_fma_f32 v[52:53], v[102:103], v[118:119], v[54:55] op_sel_hi:[1,0,1]
	v_pk_mul_f32 v[0:1], v[52:53], v[4:5] op_sel_hi:[0,1]
	v_pk_fma_f32 v[0:1], v[52:53], v[6:7], v[0:1] op_sel:[1,0,0]
	v_pk_mul_f32 v[10:11], v[110:111], v[10:11] op_sel_hi:[0,1]
	ds_read_b128 v[4:7], v90 offset:0x4800
	v_add_f32_dpp v0, v0, v0 quad_perm:[1,0,3,2] row_mask:0xf bank_mask:0xf bound_ctrl:1
	v_add_f32_dpp v1, v1, v1 quad_perm:[1,0,3,2] row_mask:0xf bank_mask:0xf bound_ctrl:1
	v_pk_fma_f32 v[54:55], v[52:53], v[8:9], v[10:11]
	v_add_f32_dpp v0, v0, v0 quad_perm:[2,3,0,1] row_mask:0xf bank_mask:0xf bound_ctrl:1
	ds_read_b128 v[8:11], v90 offset:0x800
	s_nop 0
	v_add_f32_dpp v0, v0, v0 row_half_mirror row_mask:0xf bank_mask:0xf bound_ctrl:1
	s_nop 0
	s_nop 0
	v_add_f32_dpp v2, v0, v0 row_mirror row_mask:0xf bank_mask:0xf bound_ctrl:1
	v_add_f32_dpp v0, v0, v0 row_mirror row_mask:0xf bank_mask:0xf bound_ctrl:1
	ds_read2st64_b32 v[108:109], v89 offset0:196 offset1:197
	s_waitcnt lgkmcnt(3)
	v_permlane16_swap_b32_e32 v0, v2
	v_add_f32_e32 v0, v0, v2
	v_pk_fma_f32 v[52:53], v[104:105], v[0:1], v[54:55] op_sel_hi:[1,0,1]
	v_pk_mul_f32 v[118:119], v[52:53], v[112:113] op_sel_hi:[0,1]
	v_pk_fma_f32 v[118:119], v[52:53], v[114:115], v[118:119] op_sel:[1,0,0]
	v_pk_mul_f32 v[98:99], v[110:111], v[98:99] op_sel:[1,0]
	ds_read_b128 v[112:115], v90 offset:0x4a00
	v_add_f32_dpp v118, v118, v118 quad_perm:[1,0,3,2] row_mask:0xf bank_mask:0xf bound_ctrl:1
	v_add_f32_dpp v119, v119, v119 quad_perm:[1,0,3,2] row_mask:0xf bank_mask:0xf bound_ctrl:1
	v_pk_fma_f32 v[54:55], v[52:53], v[96:97], v[98:99]
	v_add_f32_dpp v118, v118, v118 quad_perm:[2,3,0,1] row_mask:0xf bank_mask:0xf bound_ctrl:1
	ds_read_b128 v[96:99], v90 offset:0xa00
	s_nop 0
	v_add_f32_dpp v118, v118, v118 row_half_mirror row_mask:0xf bank_mask:0xf bound_ctrl:1
	ds_write2_b32 v93, v1, v119 offset0:72 offset1:108
	s_nop 0
	v_add_f32_dpp v2, v118, v118 row_mirror row_mask:0xf bank_mask:0xf bound_ctrl:1
	v_add_f32_dpp v118, v118, v118 row_mirror row_mask:0xf bank_mask:0xf bound_ctrl:1
	ds_read2st64_b64 v[100:103], v88 offset0:68 offset1:69
	s_waitcnt lgkmcnt(4)
	v_permlane16_swap_b32_e32 v118, v2
	v_add_f32_e32 v118, v118, v2
	v_pk_fma_f32 v[52:53], v[106:107], v[118:119], v[54:55] op_sel_hi:[1,0,1]
	v_pk_mul_f32 v[0:1], v[52:53], v[4:5] op_sel_hi:[0,1]
	v_pk_fma_f32 v[0:1], v[52:53], v[6:7], v[0:1] op_sel:[1,0,0]
	v_pk_mul_f32 v[10:11], v[108:109], v[10:11] op_sel_hi:[0,1]
	ds_read_b128 v[4:7], v90 offset:0x4c00
	v_add_f32_dpp v0, v0, v0 quad_perm:[1,0,3,2] row_mask:0xf bank_mask:0xf bound_ctrl:1
	v_add_f32_dpp v1, v1, v1 quad_perm:[1,0,3,2] row_mask:0xf bank_mask:0xf bound_ctrl:1
	v_pk_fma_f32 v[54:55], v[52:53], v[8:9], v[10:11]
	v_add_f32_dpp v0, v0, v0 quad_perm:[2,3,0,1] row_mask:0xf bank_mask:0xf bound_ctrl:1
	ds_read_b128 v[8:11], v90 offset:0xc00
	s_nop 0
	v_add_f32_dpp v0, v0, v0 row_half_mirror row_mask:0xf bank_mask:0xf bound_ctrl:1
	s_nop 0
	s_nop 0
	v_add_f32_dpp v2, v0, v0 row_mirror row_mask:0xf bank_mask:0xf bound_ctrl:1
	v_add_f32_dpp v0, v0, v0 row_mirror row_mask:0xf bank_mask:0xf bound_ctrl:1
	ds_read2st64_b32 v[110:111], v89 offset0:198 offset1:199
	s_waitcnt lgkmcnt(3)
	v_permlane16_swap_b32_e32 v0, v2
	v_add_f32_e32 v0, v0, v2
	v_pk_fma_f32 v[52:53], v[100:101], v[0:1], v[54:55] op_sel_hi:[1,0,1]
	v_pk_mul_f32 v[118:119], v[52:53], v[112:113] op_sel_hi:[0,1]
	v_pk_fma_f32 v[118:119], v[52:53], v[114:115], v[118:119] op_sel:[1,0,0]
	v_pk_mul_f32 v[98:99], v[108:109], v[98:99] op_sel:[1,0]
	ds_read_b128 v[112:115], v90 offset:0x4e00
	v_add_f32_dpp v118, v118, v118 quad_perm:[1,0,3,2] row_mask:0xf bank_mask:0xf bound_ctrl:1
	v_add_f32_dpp v119, v119, v119 quad_perm:[1,0,3,2] row_mask:0xf bank_mask:0xf bound_ctrl:1
	v_pk_fma_f32 v[54:55], v[52:53], v[96:97], v[98:99]
	v_add_f32_dpp v118, v118, v118 quad_perm:[2,3,0,1] row_mask:0xf bank_mask:0xf bound_ctrl:1
	ds_read_b128 v[96:99], v90 offset:0xe00
	s_nop 0
	v_add_f32_dpp v118, v118, v118 row_half_mirror row_mask:0xf bank_mask:0xf bound_ctrl:1
	ds_write2_b32 v93, v1, v119 offset0:144 offset1:180
	s_nop 0
	v_add_f32_dpp v2, v118, v118 row_mirror row_mask:0xf bank_mask:0xf bound_ctrl:1
	v_add_f32_dpp v118, v118, v118 row_mirror row_mask:0xf bank_mask:0xf bound_ctrl:1
	ds_read2st64_b64 v[104:107], v88 offset0:70 offset1:71
	s_waitcnt lgkmcnt(4)
	v_permlane16_swap_b32_e32 v118, v2
	v_add_f32_e32 v118, v118, v2
	v_pk_fma_f32 v[52:53], v[102:103], v[118:119], v[54:55] op_sel_hi:[1,0,1]
	v_pk_mul_f32 v[0:1], v[52:53], v[4:5] op_sel_hi:[0,1]
	v_pk_fma_f32 v[0:1], v[52:53], v[6:7], v[0:1] op_sel:[1,0,0]
	v_pk_mul_f32 v[10:11], v[110:111], v[10:11] op_sel_hi:[0,1]
	ds_read_b128 v[4:7], v90 offset:0x5000
	v_add_f32_dpp v0, v0, v0 quad_perm:[1,0,3,2] row_mask:0xf bank_mask:0xf bound_ctrl:1
	v_add_f32_dpp v1, v1, v1 quad_perm:[1,0,3,2] row_mask:0xf bank_mask:0xf bound_ctrl:1
	v_pk_fma_f32 v[54:55], v[52:53], v[8:9], v[10:11]
	v_add_f32_dpp v0, v0, v0 quad_perm:[2,3,0,1] row_mask:0xf bank_mask:0xf bound_ctrl:1
	ds_read_b128 v[8:11], v90 offset:0x1000
	s_nop 0
	v_add_f32_dpp v0, v0, v0 row_half_mirror row_mask:0xf bank_mask:0xf bound_ctrl:1
	s_nop 0
	s_nop 0
	v_add_f32_dpp v2, v0, v0 row_mirror row_mask:0xf bank_mask:0xf bound_ctrl:1
	v_add_f32_dpp v0, v0, v0 row_mirror row_mask:0xf bank_mask:0xf bound_ctrl:1
	ds_read2st64_b32 v[108:109], v89 offset0:200 offset1:201
	s_waitcnt lgkmcnt(3)
	v_permlane16_swap_b32_e32 v0, v2
	v_add_f32_e32 v0, v0, v2
	v_pk_fma_f32 v[52:53], v[104:105], v[0:1], v[54:55] op_sel_hi:[1,0,1]
	v_pk_mul_f32 v[118:119], v[52:53], v[112:113] op_sel_hi:[0,1]
	v_pk_fma_f32 v[118:119], v[52:53], v[114:115], v[118:119] op_sel:[1,0,0]
	v_pk_mul_f32 v[98:99], v[110:111], v[98:99] op_sel:[1,0]
	ds_read_b128 v[112:115], v90 offset:0x5200
	v_add_f32_dpp v118, v118, v118 quad_perm:[1,0,3,2] row_mask:0xf bank_mask:0xf bound_ctrl:1
	v_add_f32_dpp v119, v119, v119 quad_perm:[1,0,3,2] row_mask:0xf bank_mask:0xf bound_ctrl:1
	v_pk_fma_f32 v[54:55], v[52:53], v[96:97], v[98:99]
	v_add_f32_dpp v118, v118, v118 quad_perm:[2,3,0,1] row_mask:0xf bank_mask:0xf bound_ctrl:1
	ds_read_b128 v[96:99], v90 offset:0x1200
	s_nop 0
	v_add_f32_dpp v118, v118, v118 row_half_mirror row_mask:0xf bank_mask:0xf bound_ctrl:1
	ds_write2_b32 v93, v1, v119 offset0:216 offset1:252
	s_nop 0
	v_add_f32_dpp v2, v118, v118 row_mirror row_mask:0xf bank_mask:0xf bound_ctrl:1
	v_add_f32_dpp v118, v118, v118 row_mirror row_mask:0xf bank_mask:0xf bound_ctrl:1
	ds_read2st64_b64 v[100:103], v88 offset0:72 offset1:73
	s_waitcnt lgkmcnt(4)
	v_permlane16_swap_b32_e32 v118, v2
	v_add_f32_e32 v118, v118, v2
	v_pk_fma_f32 v[52:53], v[106:107], v[118:119], v[54:55] op_sel_hi:[1,0,1]
	v_pk_mul_f32 v[0:1], v[52:53], v[4:5] op_sel_hi:[0,1]
	v_pk_fma_f32 v[0:1], v[52:53], v[6:7], v[0:1] op_sel:[1,0,0]
	v_pk_mul_f32 v[10:11], v[108:109], v[10:11] op_sel_hi:[0,1]
	ds_read_b128 v[4:7], v90 offset:0x5400
	v_add_f32_dpp v0, v0, v0 quad_perm:[1,0,3,2] row_mask:0xf bank_mask:0xf bound_ctrl:1
	v_add_f32_dpp v1, v1, v1 quad_perm:[1,0,3,2] row_mask:0xf bank_mask:0xf bound_ctrl:1
	v_pk_fma_f32 v[54:55], v[52:53], v[8:9], v[10:11]
	v_add_f32_dpp v0, v0, v0 quad_perm:[2,3,0,1] row_mask:0xf bank_mask:0xf bound_ctrl:1
	ds_read_b128 v[8:11], v90 offset:0x1400
	s_nop 0
	v_add_f32_dpp v0, v0, v0 row_half_mirror row_mask:0xf bank_mask:0xf bound_ctrl:1
	v_add_u32_e32 v93, 0x480, v93
	s_nop 0
	v_add_f32_dpp v2, v0, v0 row_mirror row_mask:0xf bank_mask:0xf bound_ctrl:1
	v_add_f32_dpp v0, v0, v0 row_mirror row_mask:0xf bank_mask:0xf bound_ctrl:1
	ds_read2st64_b32 v[110:111], v89 offset0:202 offset1:203
	s_waitcnt lgkmcnt(3)
	v_permlane16_swap_b32_e32 v0, v2
	v_add_f32_e32 v0, v0, v2
	v_pk_fma_f32 v[52:53], v[100:101], v[0:1], v[54:55] op_sel_hi:[1,0,1]
	v_pk_mul_f32 v[118:119], v[52:53], v[112:113] op_sel_hi:[0,1]
	v_pk_fma_f32 v[118:119], v[52:53], v[114:115], v[118:119] op_sel:[1,0,0]
	v_pk_mul_f32 v[98:99], v[108:109], v[98:99] op_sel:[1,0]
	ds_read_b128 v[112:115], v90 offset:0x5600
	v_add_f32_dpp v118, v118, v118 quad_perm:[1,0,3,2] row_mask:0xf bank_mask:0xf bound_ctrl:1
	v_add_f32_dpp v119, v119, v119 quad_perm:[1,0,3,2] row_mask:0xf bank_mask:0xf bound_ctrl:1
	v_pk_fma_f32 v[54:55], v[52:53], v[96:97], v[98:99]
	v_add_f32_dpp v118, v118, v118 quad_perm:[2,3,0,1] row_mask:0xf bank_mask:0xf bound_ctrl:1
	ds_read_b128 v[96:99], v90 offset:0x1600
	s_nop 0
	v_add_f32_dpp v118, v118, v118 row_half_mirror row_mask:0xf bank_mask:0xf bound_ctrl:1
	ds_write2_b32 v93, v1, v119 offset0:0 offset1:36
	s_nop 0
	v_add_f32_dpp v2, v118, v118 row_mirror row_mask:0xf bank_mask:0xf bound_ctrl:1
	v_add_f32_dpp v118, v118, v118 row_mirror row_mask:0xf bank_mask:0xf bound_ctrl:1
	ds_read2st64_b64 v[104:107], v88 offset0:74 offset1:75
	s_waitcnt lgkmcnt(4)
	v_permlane16_swap_b32_e32 v118, v2
	v_add_f32_e32 v118, v118, v2
	v_pk_fma_f32 v[52:53], v[102:103], v[118:119], v[54:55] op_sel_hi:[1,0,1]
	v_pk_mul_f32 v[0:1], v[52:53], v[4:5] op_sel_hi:[0,1]
	v_pk_fma_f32 v[0:1], v[52:53], v[6:7], v[0:1] op_sel:[1,0,0]
	v_pk_mul_f32 v[10:11], v[110:111], v[10:11] op_sel_hi:[0,1]
	ds_read_b128 v[4:7], v90 offset:0x5800
	v_add_f32_dpp v0, v0, v0 quad_perm:[1,0,3,2] row_mask:0xf bank_mask:0xf bound_ctrl:1
	v_add_f32_dpp v1, v1, v1 quad_perm:[1,0,3,2] row_mask:0xf bank_mask:0xf bound_ctrl:1
	v_pk_fma_f32 v[54:55], v[52:53], v[8:9], v[10:11]
	v_add_f32_dpp v0, v0, v0 quad_perm:[2,3,0,1] row_mask:0xf bank_mask:0xf bound_ctrl:1
	ds_read_b128 v[8:11], v90 offset:0x1800
	s_nop 0
	v_add_f32_dpp v0, v0, v0 row_half_mirror row_mask:0xf bank_mask:0xf bound_ctrl:1
	s_nop 0
	s_nop 0
	v_add_f32_dpp v2, v0, v0 row_mirror row_mask:0xf bank_mask:0xf bound_ctrl:1
	v_add_f32_dpp v0, v0, v0 row_mirror row_mask:0xf bank_mask:0xf bound_ctrl:1
	ds_read2st64_b32 v[108:109], v89 offset0:204 offset1:205
	s_waitcnt lgkmcnt(3)
	v_permlane16_swap_b32_e32 v0, v2
	v_add_f32_e32 v0, v0, v2
	v_pk_fma_f32 v[52:53], v[104:105], v[0:1], v[54:55] op_sel_hi:[1,0,1]
	v_pk_mul_f32 v[118:119], v[52:53], v[112:113] op_sel_hi:[0,1]
	v_pk_fma_f32 v[118:119], v[52:53], v[114:115], v[118:119] op_sel:[1,0,0]
	v_pk_mul_f32 v[98:99], v[110:111], v[98:99] op_sel:[1,0]
	ds_read_b128 v[112:115], v90 offset:0x5a00
	v_add_f32_dpp v118, v118, v118 quad_perm:[1,0,3,2] row_mask:0xf bank_mask:0xf bound_ctrl:1
	v_add_f32_dpp v119, v119, v119 quad_perm:[1,0,3,2] row_mask:0xf bank_mask:0xf bound_ctrl:1
	v_pk_fma_f32 v[54:55], v[52:53], v[96:97], v[98:99]
	v_add_f32_dpp v118, v118, v118 quad_perm:[2,3,0,1] row_mask:0xf bank_mask:0xf bound_ctrl:1
	ds_read_b128 v[96:99], v90 offset:0x1a00
	s_nop 0
	v_add_f32_dpp v118, v118, v118 row_half_mirror row_mask:0xf bank_mask:0xf bound_ctrl:1
	ds_write2_b32 v93, v1, v119 offset0:72 offset1:108
	s_nop 0
	v_add_f32_dpp v2, v118, v118 row_mirror row_mask:0xf bank_mask:0xf bound_ctrl:1
	v_add_f32_dpp v118, v118, v118 row_mirror row_mask:0xf bank_mask:0xf bound_ctrl:1
	ds_read2st64_b64 v[100:103], v88 offset0:76 offset1:77
	s_waitcnt lgkmcnt(4)
	v_permlane16_swap_b32_e32 v118, v2
	v_add_f32_e32 v118, v118, v2
	v_pk_fma_f32 v[52:53], v[106:107], v[118:119], v[54:55] op_sel_hi:[1,0,1]
	v_pk_mul_f32 v[0:1], v[52:53], v[4:5] op_sel_hi:[0,1]
	v_pk_fma_f32 v[0:1], v[52:53], v[6:7], v[0:1] op_sel:[1,0,0]
	v_pk_mul_f32 v[10:11], v[108:109], v[10:11] op_sel_hi:[0,1]
	ds_read_b128 v[4:7], v90 offset:0x5c00
	v_add_f32_dpp v0, v0, v0 quad_perm:[1,0,3,2] row_mask:0xf bank_mask:0xf bound_ctrl:1
	v_add_f32_dpp v1, v1, v1 quad_perm:[1,0,3,2] row_mask:0xf bank_mask:0xf bound_ctrl:1
	v_pk_fma_f32 v[54:55], v[52:53], v[8:9], v[10:11]
	v_add_f32_dpp v0, v0, v0 quad_perm:[2,3,0,1] row_mask:0xf bank_mask:0xf bound_ctrl:1
	ds_read_b128 v[8:11], v90 offset:0x1c00
	s_nop 0
	v_add_f32_dpp v0, v0, v0 row_half_mirror row_mask:0xf bank_mask:0xf bound_ctrl:1
	s_nop 0
	s_nop 0
	v_add_f32_dpp v2, v0, v0 row_mirror row_mask:0xf bank_mask:0xf bound_ctrl:1
	v_add_f32_dpp v0, v0, v0 row_mirror row_mask:0xf bank_mask:0xf bound_ctrl:1
	ds_read2st64_b32 v[110:111], v89 offset0:206 offset1:207
	s_waitcnt lgkmcnt(3)
	v_permlane16_swap_b32_e32 v0, v2
	v_add_f32_e32 v0, v0, v2
	v_pk_fma_f32 v[52:53], v[100:101], v[0:1], v[54:55] op_sel_hi:[1,0,1]
	v_pk_mul_f32 v[118:119], v[52:53], v[112:113] op_sel_hi:[0,1]
	v_pk_fma_f32 v[118:119], v[52:53], v[114:115], v[118:119] op_sel:[1,0,0]
	v_pk_mul_f32 v[98:99], v[108:109], v[98:99] op_sel:[1,0]
	ds_read_b128 v[112:115], v90 offset:0x5e00
	v_add_f32_dpp v118, v118, v118 quad_perm:[1,0,3,2] row_mask:0xf bank_mask:0xf bound_ctrl:1
	v_add_f32_dpp v119, v119, v119 quad_perm:[1,0,3,2] row_mask:0xf bank_mask:0xf bound_ctrl:1
	v_pk_fma_f32 v[54:55], v[52:53], v[96:97], v[98:99]
	v_add_f32_dpp v118, v118, v118 quad_perm:[2,3,0,1] row_mask:0xf bank_mask:0xf bound_ctrl:1
	ds_read_b128 v[96:99], v90 offset:0x1e00
	s_nop 0
	v_add_f32_dpp v118, v118, v118 row_half_mirror row_mask:0xf bank_mask:0xf bound_ctrl:1
	ds_write2_b32 v93, v1, v119 offset0:144 offset1:180
	s_nop 0
	v_add_f32_dpp v2, v118, v118 row_mirror row_mask:0xf bank_mask:0xf bound_ctrl:1
	v_add_f32_dpp v118, v118, v118 row_mirror row_mask:0xf bank_mask:0xf bound_ctrl:1
	ds_read2st64_b64 v[104:107], v88 offset0:78 offset1:79
	s_waitcnt lgkmcnt(4)
	v_permlane16_swap_b32_e32 v118, v2
	v_add_f32_e32 v118, v118, v2
	v_pk_fma_f32 v[52:53], v[102:103], v[118:119], v[54:55] op_sel_hi:[1,0,1]
	v_pk_mul_f32 v[0:1], v[52:53], v[4:5] op_sel_hi:[0,1]
	v_pk_fma_f32 v[0:1], v[52:53], v[6:7], v[0:1] op_sel:[1,0,0]
	v_pk_mul_f32 v[10:11], v[110:111], v[10:11] op_sel_hi:[0,1]
	ds_read_b128 v[4:7], v90 offset:0x6000
	v_add_f32_dpp v0, v0, v0 quad_perm:[1,0,3,2] row_mask:0xf bank_mask:0xf bound_ctrl:1
	v_add_f32_dpp v1, v1, v1 quad_perm:[1,0,3,2] row_mask:0xf bank_mask:0xf bound_ctrl:1
	v_pk_fma_f32 v[54:55], v[52:53], v[8:9], v[10:11]
	v_add_f32_dpp v0, v0, v0 quad_perm:[2,3,0,1] row_mask:0xf bank_mask:0xf bound_ctrl:1
	ds_read_b128 v[8:11], v90 offset:0x2000
	s_nop 0
	v_add_f32_dpp v0, v0, v0 row_half_mirror row_mask:0xf bank_mask:0xf bound_ctrl:1
	s_nop 0
	s_nop 0
	v_add_f32_dpp v2, v0, v0 row_mirror row_mask:0xf bank_mask:0xf bound_ctrl:1
	v_add_f32_dpp v0, v0, v0 row_mirror row_mask:0xf bank_mask:0xf bound_ctrl:1
	ds_read2st64_b32 v[108:109], v89 offset0:208 offset1:209
	s_waitcnt lgkmcnt(3)
	v_permlane16_swap_b32_e32 v0, v2
	v_add_f32_e32 v0, v0, v2
	v_pk_fma_f32 v[52:53], v[104:105], v[0:1], v[54:55] op_sel_hi:[1,0,1]
	v_pk_mul_f32 v[118:119], v[52:53], v[112:113] op_sel_hi:[0,1]
	v_pk_fma_f32 v[118:119], v[52:53], v[114:115], v[118:119] op_sel:[1,0,0]
	v_pk_mul_f32 v[98:99], v[110:111], v[98:99] op_sel:[1,0]
	ds_read_b128 v[112:115], v90 offset:0x6200
	v_add_f32_dpp v118, v118, v118 quad_perm:[1,0,3,2] row_mask:0xf bank_mask:0xf bound_ctrl:1
	v_add_f32_dpp v119, v119, v119 quad_perm:[1,0,3,2] row_mask:0xf bank_mask:0xf bound_ctrl:1
	v_pk_fma_f32 v[54:55], v[52:53], v[96:97], v[98:99]
	v_add_f32_dpp v118, v118, v118 quad_perm:[2,3,0,1] row_mask:0xf bank_mask:0xf bound_ctrl:1
	ds_read_b128 v[96:99], v90 offset:0x2200
	s_nop 0
	v_add_f32_dpp v118, v118, v118 row_half_mirror row_mask:0xf bank_mask:0xf bound_ctrl:1
	ds_write2_b32 v93, v1, v119 offset0:216 offset1:252
	s_nop 0
	v_add_f32_dpp v2, v118, v118 row_mirror row_mask:0xf bank_mask:0xf bound_ctrl:1
	v_add_f32_dpp v118, v118, v118 row_mirror row_mask:0xf bank_mask:0xf bound_ctrl:1
	ds_read2st64_b64 v[100:103], v88 offset0:80 offset1:81
	s_waitcnt lgkmcnt(4)
	v_permlane16_swap_b32_e32 v118, v2
	v_add_f32_e32 v118, v118, v2
	v_pk_fma_f32 v[52:53], v[106:107], v[118:119], v[54:55] op_sel_hi:[1,0,1]
	s_cmp_eq_u32 s88, 0x800000
	s_cbranch_scc1 .LBB0_684
	v_pk_mul_f32 v[0:1], v[52:53], v[4:5] op_sel_hi:[0,1]
	v_pk_fma_f32 v[0:1], v[52:53], v[6:7], v[0:1] op_sel:[1,0,0]
	v_pk_mul_f32 v[10:11], v[108:109], v[10:11] op_sel_hi:[0,1]
	ds_read_b128 v[4:7], v90 offset:0x6400
	v_add_f32_dpp v0, v0, v0 quad_perm:[1,0,3,2] row_mask:0xf bank_mask:0xf bound_ctrl:1
	v_add_f32_dpp v1, v1, v1 quad_perm:[1,0,3,2] row_mask:0xf bank_mask:0xf bound_ctrl:1
	v_pk_fma_f32 v[54:55], v[52:53], v[8:9], v[10:11]
	v_add_f32_dpp v0, v0, v0 quad_perm:[2,3,0,1] row_mask:0xf bank_mask:0xf bound_ctrl:1
	ds_read_b128 v[8:11], v90 offset:0x2400
	s_nop 0
	v_add_f32_dpp v0, v0, v0 row_half_mirror row_mask:0xf bank_mask:0xf bound_ctrl:1
	v_add_u32_e32 v93, 0x480, v93
	s_nop 0
	v_add_f32_dpp v2, v0, v0 row_mirror row_mask:0xf bank_mask:0xf bound_ctrl:1
	v_add_f32_dpp v0, v0, v0 row_mirror row_mask:0xf bank_mask:0xf bound_ctrl:1
	ds_read2st64_b32 v[110:111], v89 offset0:210 offset1:211
	s_waitcnt lgkmcnt(3)
	v_permlane16_swap_b32_e32 v0, v2
	v_add_f32_e32 v0, v0, v2
	v_pk_fma_f32 v[52:53], v[100:101], v[0:1], v[54:55] op_sel_hi:[1,0,1]
	v_pk_mul_f32 v[118:119], v[52:53], v[112:113] op_sel_hi:[0,1]
	v_pk_fma_f32 v[118:119], v[52:53], v[114:115], v[118:119] op_sel:[1,0,0]
	v_pk_mul_f32 v[98:99], v[108:109], v[98:99] op_sel:[1,0]
	ds_read_b128 v[112:115], v90 offset:0x6600
	v_add_f32_dpp v118, v118, v118 quad_perm:[1,0,3,2] row_mask:0xf bank_mask:0xf bound_ctrl:1
	v_add_f32_dpp v119, v119, v119 quad_perm:[1,0,3,2] row_mask:0xf bank_mask:0xf bound_ctrl:1
	v_pk_fma_f32 v[54:55], v[52:53], v[96:97], v[98:99]
	v_add_f32_dpp v118, v118, v118 quad_perm:[2,3,0,1] row_mask:0xf bank_mask:0xf bound_ctrl:1
	ds_read_b128 v[96:99], v90 offset:0x2600
	s_nop 0
	v_add_f32_dpp v118, v118, v118 row_half_mirror row_mask:0xf bank_mask:0xf bound_ctrl:1
	ds_write2_b32 v93, v1, v119 offset0:0 offset1:36
	s_nop 0
	v_add_f32_dpp v2, v118, v118 row_mirror row_mask:0xf bank_mask:0xf bound_ctrl:1
	v_add_f32_dpp v118, v118, v118 row_mirror row_mask:0xf bank_mask:0xf bound_ctrl:1
	ds_read2st64_b64 v[104:107], v88 offset0:82 offset1:83
	s_waitcnt lgkmcnt(4)
	v_permlane16_swap_b32_e32 v118, v2
	v_add_f32_e32 v118, v118, v2
	v_pk_fma_f32 v[52:53], v[102:103], v[118:119], v[54:55] op_sel_hi:[1,0,1]
	v_pk_mul_f32 v[0:1], v[52:53], v[4:5] op_sel_hi:[0,1]
	v_pk_fma_f32 v[0:1], v[52:53], v[6:7], v[0:1] op_sel:[1,0,0]
	v_pk_mul_f32 v[10:11], v[110:111], v[10:11] op_sel_hi:[0,1]
	ds_read_b128 v[4:7], v90 offset:0x6800
	v_add_f32_dpp v0, v0, v0 quad_perm:[1,0,3,2] row_mask:0xf bank_mask:0xf bound_ctrl:1
	v_add_f32_dpp v1, v1, v1 quad_perm:[1,0,3,2] row_mask:0xf bank_mask:0xf bound_ctrl:1
	v_pk_fma_f32 v[54:55], v[52:53], v[8:9], v[10:11]
	v_add_f32_dpp v0, v0, v0 quad_perm:[2,3,0,1] row_mask:0xf bank_mask:0xf bound_ctrl:1
	ds_read_b128 v[8:11], v90 offset:0x2800
	s_nop 0
	v_add_f32_dpp v0, v0, v0 row_half_mirror row_mask:0xf bank_mask:0xf bound_ctrl:1
	s_nop 0
	s_nop 0
	v_add_f32_dpp v2, v0, v0 row_mirror row_mask:0xf bank_mask:0xf bound_ctrl:1
	v_add_f32_dpp v0, v0, v0 row_mirror row_mask:0xf bank_mask:0xf bound_ctrl:1
	ds_read2st64_b32 v[108:109], v89 offset0:212 offset1:213
	s_waitcnt lgkmcnt(3)
	v_permlane16_swap_b32_e32 v0, v2
	v_add_f32_e32 v0, v0, v2
	v_pk_fma_f32 v[52:53], v[104:105], v[0:1], v[54:55] op_sel_hi:[1,0,1]
	v_pk_mul_f32 v[118:119], v[52:53], v[112:113] op_sel_hi:[0,1]
	v_pk_fma_f32 v[118:119], v[52:53], v[114:115], v[118:119] op_sel:[1,0,0]
	v_pk_mul_f32 v[98:99], v[110:111], v[98:99] op_sel:[1,0]
	ds_read_b128 v[112:115], v90 offset:0x6a00
	v_add_f32_dpp v118, v118, v118 quad_perm:[1,0,3,2] row_mask:0xf bank_mask:0xf bound_ctrl:1
	v_add_f32_dpp v119, v119, v119 quad_perm:[1,0,3,2] row_mask:0xf bank_mask:0xf bound_ctrl:1
	v_pk_fma_f32 v[54:55], v[52:53], v[96:97], v[98:99]
	v_add_f32_dpp v118, v118, v118 quad_perm:[2,3,0,1] row_mask:0xf bank_mask:0xf bound_ctrl:1
	ds_read_b128 v[96:99], v90 offset:0x2a00
	s_nop 0
	v_add_f32_dpp v118, v118, v118 row_half_mirror row_mask:0xf bank_mask:0xf bound_ctrl:1
	ds_write2_b32 v93, v1, v119 offset0:72 offset1:108
	s_nop 0
	v_add_f32_dpp v2, v118, v118 row_mirror row_mask:0xf bank_mask:0xf bound_ctrl:1
	v_add_f32_dpp v118, v118, v118 row_mirror row_mask:0xf bank_mask:0xf bound_ctrl:1
	ds_read2st64_b64 v[100:103], v88 offset0:84 offset1:85
	s_waitcnt lgkmcnt(4)
	v_permlane16_swap_b32_e32 v118, v2
	v_add_f32_e32 v118, v118, v2
	v_pk_fma_f32 v[52:53], v[106:107], v[118:119], v[54:55] op_sel_hi:[1,0,1]
	v_pk_mul_f32 v[0:1], v[52:53], v[4:5] op_sel_hi:[0,1]
	v_pk_fma_f32 v[0:1], v[52:53], v[6:7], v[0:1] op_sel:[1,0,0]
	v_pk_mul_f32 v[10:11], v[108:109], v[10:11] op_sel_hi:[0,1]
	ds_read_b128 v[4:7], v90 offset:0x6c00
	v_add_f32_dpp v0, v0, v0 quad_perm:[1,0,3,2] row_mask:0xf bank_mask:0xf bound_ctrl:1
	v_add_f32_dpp v1, v1, v1 quad_perm:[1,0,3,2] row_mask:0xf bank_mask:0xf bound_ctrl:1
	v_pk_fma_f32 v[54:55], v[52:53], v[8:9], v[10:11]
	v_add_f32_dpp v0, v0, v0 quad_perm:[2,3,0,1] row_mask:0xf bank_mask:0xf bound_ctrl:1
	ds_read_b128 v[8:11], v90 offset:0x2c00
	s_nop 0
	v_add_f32_dpp v0, v0, v0 row_half_mirror row_mask:0xf bank_mask:0xf bound_ctrl:1
	s_nop 0
	s_nop 0
	v_add_f32_dpp v2, v0, v0 row_mirror row_mask:0xf bank_mask:0xf bound_ctrl:1
	v_add_f32_dpp v0, v0, v0 row_mirror row_mask:0xf bank_mask:0xf bound_ctrl:1
	ds_read2st64_b32 v[110:111], v89 offset0:214 offset1:215
	s_waitcnt lgkmcnt(3)
	v_permlane16_swap_b32_e32 v0, v2
	v_add_f32_e32 v0, v0, v2
	v_pk_fma_f32 v[52:53], v[100:101], v[0:1], v[54:55] op_sel_hi:[1,0,1]
	v_pk_mul_f32 v[118:119], v[52:53], v[112:113] op_sel_hi:[0,1]
	v_pk_fma_f32 v[118:119], v[52:53], v[114:115], v[118:119] op_sel:[1,0,0]
	v_pk_mul_f32 v[98:99], v[108:109], v[98:99] op_sel:[1,0]
	ds_read_b128 v[112:115], v90 offset:0x6e00
	v_add_f32_dpp v118, v118, v118 quad_perm:[1,0,3,2] row_mask:0xf bank_mask:0xf bound_ctrl:1
	v_add_f32_dpp v119, v119, v119 quad_perm:[1,0,3,2] row_mask:0xf bank_mask:0xf bound_ctrl:1
	v_pk_fma_f32 v[54:55], v[52:53], v[96:97], v[98:99]
	v_add_f32_dpp v118, v118, v118 quad_perm:[2,3,0,1] row_mask:0xf bank_mask:0xf bound_ctrl:1
	ds_read_b128 v[96:99], v90 offset:0x2e00
	s_nop 0
	v_add_f32_dpp v118, v118, v118 row_half_mirror row_mask:0xf bank_mask:0xf bound_ctrl:1
	ds_write2_b32 v93, v1, v119 offset0:144 offset1:180
	s_nop 0
	v_add_f32_dpp v2, v118, v118 row_mirror row_mask:0xf bank_mask:0xf bound_ctrl:1
	v_add_f32_dpp v118, v118, v118 row_mirror row_mask:0xf bank_mask:0xf bound_ctrl:1
	ds_read2st64_b64 v[104:107], v88 offset0:86 offset1:87
	s_waitcnt lgkmcnt(4)
	v_permlane16_swap_b32_e32 v118, v2
	v_add_f32_e32 v118, v118, v2
	v_pk_fma_f32 v[52:53], v[102:103], v[118:119], v[54:55] op_sel_hi:[1,0,1]
	v_pk_mul_f32 v[0:1], v[52:53], v[4:5] op_sel_hi:[0,1]
	v_pk_fma_f32 v[0:1], v[52:53], v[6:7], v[0:1] op_sel:[1,0,0]
	v_pk_mul_f32 v[10:11], v[110:111], v[10:11] op_sel_hi:[0,1]
	ds_read_b128 v[4:7], v90 offset:0x7000
	v_add_f32_dpp v0, v0, v0 quad_perm:[1,0,3,2] row_mask:0xf bank_mask:0xf bound_ctrl:1
	v_add_f32_dpp v1, v1, v1 quad_perm:[1,0,3,2] row_mask:0xf bank_mask:0xf bound_ctrl:1
	v_pk_fma_f32 v[54:55], v[52:53], v[8:9], v[10:11]
	v_add_f32_dpp v0, v0, v0 quad_perm:[2,3,0,1] row_mask:0xf bank_mask:0xf bound_ctrl:1
	ds_read_b128 v[8:11], v90 offset:0x3000
	s_nop 0
	v_add_f32_dpp v0, v0, v0 row_half_mirror row_mask:0xf bank_mask:0xf bound_ctrl:1
	s_nop 0
	s_nop 0
	v_add_f32_dpp v2, v0, v0 row_mirror row_mask:0xf bank_mask:0xf bound_ctrl:1
	v_add_f32_dpp v0, v0, v0 row_mirror row_mask:0xf bank_mask:0xf bound_ctrl:1
	ds_read2st64_b32 v[108:109], v89 offset0:216 offset1:217
	s_waitcnt lgkmcnt(3)
	v_permlane16_swap_b32_e32 v0, v2
	v_add_f32_e32 v0, v0, v2
	v_pk_fma_f32 v[52:53], v[104:105], v[0:1], v[54:55] op_sel_hi:[1,0,1]
	v_pk_mul_f32 v[118:119], v[52:53], v[112:113] op_sel_hi:[0,1]
	v_pk_fma_f32 v[118:119], v[52:53], v[114:115], v[118:119] op_sel:[1,0,0]
	v_pk_mul_f32 v[98:99], v[110:111], v[98:99] op_sel:[1,0]
	ds_read_b128 v[112:115], v90 offset:0x7200
	v_add_f32_dpp v118, v118, v118 quad_perm:[1,0,3,2] row_mask:0xf bank_mask:0xf bound_ctrl:1
	v_add_f32_dpp v119, v119, v119 quad_perm:[1,0,3,2] row_mask:0xf bank_mask:0xf bound_ctrl:1
	v_pk_fma_f32 v[54:55], v[52:53], v[96:97], v[98:99]
	v_add_f32_dpp v118, v118, v118 quad_perm:[2,3,0,1] row_mask:0xf bank_mask:0xf bound_ctrl:1
	ds_read_b128 v[96:99], v90 offset:0x3200
	s_nop 0
	v_add_f32_dpp v118, v118, v118 row_half_mirror row_mask:0xf bank_mask:0xf bound_ctrl:1
	ds_write2_b32 v93, v1, v119 offset0:216 offset1:252
	s_nop 0
	v_add_f32_dpp v2, v118, v118 row_mirror row_mask:0xf bank_mask:0xf bound_ctrl:1
	v_add_f32_dpp v118, v118, v118 row_mirror row_mask:0xf bank_mask:0xf bound_ctrl:1
	ds_read2st64_b64 v[100:103], v88 offset0:88 offset1:89
	s_waitcnt lgkmcnt(4)
	v_permlane16_swap_b32_e32 v118, v2
	v_add_f32_e32 v118, v118, v2
	v_pk_fma_f32 v[52:53], v[106:107], v[118:119], v[54:55] op_sel_hi:[1,0,1]
	v_pk_mul_f32 v[0:1], v[52:53], v[4:5] op_sel_hi:[0,1]
	v_pk_fma_f32 v[0:1], v[52:53], v[6:7], v[0:1] op_sel:[1,0,0]
	v_pk_mul_f32 v[10:11], v[108:109], v[10:11] op_sel_hi:[0,1]
	ds_read_b128 v[4:7], v90 offset:0x7400
	v_add_f32_dpp v0, v0, v0 quad_perm:[1,0,3,2] row_mask:0xf bank_mask:0xf bound_ctrl:1
	v_add_f32_dpp v1, v1, v1 quad_perm:[1,0,3,2] row_mask:0xf bank_mask:0xf bound_ctrl:1
	v_pk_fma_f32 v[54:55], v[52:53], v[8:9], v[10:11]
	v_add_f32_dpp v0, v0, v0 quad_perm:[2,3,0,1] row_mask:0xf bank_mask:0xf bound_ctrl:1
	ds_read_b128 v[8:11], v90 offset:0x3400
	s_nop 0
	v_add_f32_dpp v0, v0, v0 row_half_mirror row_mask:0xf bank_mask:0xf bound_ctrl:1
	v_add_u32_e32 v93, 0x480, v93
	s_nop 0
	v_add_f32_dpp v2, v0, v0 row_mirror row_mask:0xf bank_mask:0xf bound_ctrl:1
	v_add_f32_dpp v0, v0, v0 row_mirror row_mask:0xf bank_mask:0xf bound_ctrl:1
	ds_read2st64_b32 v[110:111], v89 offset0:218 offset1:219
	s_waitcnt lgkmcnt(3)
	v_permlane16_swap_b32_e32 v0, v2
	v_add_f32_e32 v0, v0, v2
	v_pk_fma_f32 v[52:53], v[100:101], v[0:1], v[54:55] op_sel_hi:[1,0,1]
	v_pk_mul_f32 v[118:119], v[52:53], v[112:113] op_sel_hi:[0,1]
	v_pk_fma_f32 v[118:119], v[52:53], v[114:115], v[118:119] op_sel:[1,0,0]
	v_pk_mul_f32 v[98:99], v[108:109], v[98:99] op_sel:[1,0]
	ds_read_b128 v[112:115], v90 offset:0x7600
	v_add_f32_dpp v118, v118, v118 quad_perm:[1,0,3,2] row_mask:0xf bank_mask:0xf bound_ctrl:1
	v_add_f32_dpp v119, v119, v119 quad_perm:[1,0,3,2] row_mask:0xf bank_mask:0xf bound_ctrl:1
	v_pk_fma_f32 v[54:55], v[52:53], v[96:97], v[98:99]
	v_add_f32_dpp v118, v118, v118 quad_perm:[2,3,0,1] row_mask:0xf bank_mask:0xf bound_ctrl:1
	ds_read_b128 v[96:99], v90 offset:0x3600
	s_nop 0
	v_add_f32_dpp v118, v118, v118 row_half_mirror row_mask:0xf bank_mask:0xf bound_ctrl:1
	ds_write2_b32 v93, v1, v119 offset0:0 offset1:36
	s_nop 0
	v_add_f32_dpp v2, v118, v118 row_mirror row_mask:0xf bank_mask:0xf bound_ctrl:1
	v_add_f32_dpp v118, v118, v118 row_mirror row_mask:0xf bank_mask:0xf bound_ctrl:1
	ds_read2st64_b64 v[104:107], v88 offset0:90 offset1:91
	s_waitcnt lgkmcnt(4)
	v_permlane16_swap_b32_e32 v118, v2
	v_add_f32_e32 v118, v118, v2
	v_pk_fma_f32 v[52:53], v[102:103], v[118:119], v[54:55] op_sel_hi:[1,0,1]
	v_pk_mul_f32 v[0:1], v[52:53], v[4:5] op_sel_hi:[0,1]
	v_pk_fma_f32 v[0:1], v[52:53], v[6:7], v[0:1] op_sel:[1,0,0]
	v_pk_mul_f32 v[10:11], v[110:111], v[10:11] op_sel_hi:[0,1]
	ds_read_b128 v[4:7], v90 offset:0x7800
	v_add_f32_dpp v0, v0, v0 quad_perm:[1,0,3,2] row_mask:0xf bank_mask:0xf bound_ctrl:1
	v_add_f32_dpp v1, v1, v1 quad_perm:[1,0,3,2] row_mask:0xf bank_mask:0xf bound_ctrl:1
	v_pk_fma_f32 v[54:55], v[52:53], v[8:9], v[10:11]
	v_add_f32_dpp v0, v0, v0 quad_perm:[2,3,0,1] row_mask:0xf bank_mask:0xf bound_ctrl:1
	ds_read_b128 v[8:11], v90 offset:0x3800
	s_nop 0
	v_add_f32_dpp v0, v0, v0 row_half_mirror row_mask:0xf bank_mask:0xf bound_ctrl:1
	s_nop 0
	s_nop 0
	v_add_f32_dpp v2, v0, v0 row_mirror row_mask:0xf bank_mask:0xf bound_ctrl:1
	v_add_f32_dpp v0, v0, v0 row_mirror row_mask:0xf bank_mask:0xf bound_ctrl:1
	ds_read2st64_b32 v[108:109], v89 offset0:220 offset1:221
	s_waitcnt lgkmcnt(3)
	v_permlane16_swap_b32_e32 v0, v2
	v_add_f32_e32 v0, v0, v2
	v_pk_fma_f32 v[52:53], v[104:105], v[0:1], v[54:55] op_sel_hi:[1,0,1]
	v_pk_mul_f32 v[118:119], v[52:53], v[112:113] op_sel_hi:[0,1]
	v_pk_fma_f32 v[118:119], v[52:53], v[114:115], v[118:119] op_sel:[1,0,0]
	v_pk_mul_f32 v[98:99], v[110:111], v[98:99] op_sel:[1,0]
	ds_read_b128 v[112:115], v90 offset:0x7a00
	v_add_f32_dpp v118, v118, v118 quad_perm:[1,0,3,2] row_mask:0xf bank_mask:0xf bound_ctrl:1
	v_add_f32_dpp v119, v119, v119 quad_perm:[1,0,3,2] row_mask:0xf bank_mask:0xf bound_ctrl:1
	v_pk_fma_f32 v[54:55], v[52:53], v[96:97], v[98:99]
	v_add_f32_dpp v118, v118, v118 quad_perm:[2,3,0,1] row_mask:0xf bank_mask:0xf bound_ctrl:1
	ds_read_b128 v[96:99], v90 offset:0x3a00
	s_nop 0
	v_add_f32_dpp v118, v118, v118 row_half_mirror row_mask:0xf bank_mask:0xf bound_ctrl:1
	ds_write2_b32 v93, v1, v119 offset0:72 offset1:108
	s_nop 0
	v_add_f32_dpp v2, v118, v118 row_mirror row_mask:0xf bank_mask:0xf bound_ctrl:1
	v_add_f32_dpp v118, v118, v118 row_mirror row_mask:0xf bank_mask:0xf bound_ctrl:1
	ds_read2st64_b64 v[100:103], v88 offset0:92 offset1:93
	s_waitcnt lgkmcnt(4)
	v_permlane16_swap_b32_e32 v118, v2
	v_add_f32_e32 v118, v118, v2
	v_pk_fma_f32 v[52:53], v[106:107], v[118:119], v[54:55] op_sel_hi:[1,0,1]
	v_pk_mul_f32 v[0:1], v[52:53], v[4:5] op_sel_hi:[0,1]
	v_pk_fma_f32 v[0:1], v[52:53], v[6:7], v[0:1] op_sel:[1,0,0]
	v_pk_mul_f32 v[10:11], v[108:109], v[10:11] op_sel_hi:[0,1]
	ds_read_b128 v[4:7], v90 offset:0x7c00
	v_add_f32_dpp v0, v0, v0 quad_perm:[1,0,3,2] row_mask:0xf bank_mask:0xf bound_ctrl:1
	v_add_f32_dpp v1, v1, v1 quad_perm:[1,0,3,2] row_mask:0xf bank_mask:0xf bound_ctrl:1
	v_pk_fma_f32 v[54:55], v[52:53], v[8:9], v[10:11]
	v_add_f32_dpp v0, v0, v0 quad_perm:[2,3,0,1] row_mask:0xf bank_mask:0xf bound_ctrl:1
	ds_read_b128 v[8:11], v90 offset:0x3c00
	s_nop 0
	v_add_f32_dpp v0, v0, v0 row_half_mirror row_mask:0xf bank_mask:0xf bound_ctrl:1
	s_nop 0
	s_nop 0
	v_add_f32_dpp v2, v0, v0 row_mirror row_mask:0xf bank_mask:0xf bound_ctrl:1
	v_add_f32_dpp v0, v0, v0 row_mirror row_mask:0xf bank_mask:0xf bound_ctrl:1
	ds_read2st64_b32 v[110:111], v89 offset0:222 offset1:223
	s_waitcnt lgkmcnt(3)
	v_permlane16_swap_b32_e32 v0, v2
	v_add_f32_e32 v0, v0, v2
	v_pk_fma_f32 v[52:53], v[100:101], v[0:1], v[54:55] op_sel_hi:[1,0,1]
	v_pk_mul_f32 v[118:119], v[52:53], v[112:113] op_sel_hi:[0,1]
	v_pk_fma_f32 v[118:119], v[52:53], v[114:115], v[118:119] op_sel:[1,0,0]
	v_pk_mul_f32 v[98:99], v[108:109], v[98:99] op_sel:[1,0]
	ds_read_b128 v[112:115], v90 offset:0x7e00
	v_add_f32_dpp v118, v118, v118 quad_perm:[1,0,3,2] row_mask:0xf bank_mask:0xf bound_ctrl:1
	v_add_f32_dpp v119, v119, v119 quad_perm:[1,0,3,2] row_mask:0xf bank_mask:0xf bound_ctrl:1
	v_pk_fma_f32 v[54:55], v[52:53], v[96:97], v[98:99]
	v_add_f32_dpp v118, v118, v118 quad_perm:[2,3,0,1] row_mask:0xf bank_mask:0xf bound_ctrl:1
	ds_read_b128 v[96:99], v90 offset:0x3e00
	s_nop 0
	v_add_f32_dpp v118, v118, v118 row_half_mirror row_mask:0xf bank_mask:0xf bound_ctrl:1
	ds_write2_b32 v93, v1, v119 offset0:144 offset1:180
	s_nop 0
	v_add_f32_dpp v2, v118, v118 row_mirror row_mask:0xf bank_mask:0xf bound_ctrl:1
	v_add_f32_dpp v118, v118, v118 row_mirror row_mask:0xf bank_mask:0xf bound_ctrl:1
	ds_read2st64_b64 v[104:107], v88 offset0:94 offset1:95
	s_waitcnt lgkmcnt(4)
	v_permlane16_swap_b32_e32 v118, v2
	v_add_f32_e32 v118, v118, v2
	v_pk_fma_f32 v[52:53], v[102:103], v[118:119], v[54:55] op_sel_hi:[1,0,1]
	v_pk_mul_f32 v[0:1], v[52:53], v[4:5] op_sel_hi:[0,1]
	v_pk_fma_f32 v[0:1], v[52:53], v[6:7], v[0:1] op_sel:[1,0,0]
	v_pk_mul_f32 v[10:11], v[110:111], v[10:11] op_sel_hi:[0,1]
	s_nop 0
	v_add_f32_dpp v0, v0, v0 quad_perm:[1,0,3,2] row_mask:0xf bank_mask:0xf bound_ctrl:1
	v_add_f32_dpp v1, v1, v1 quad_perm:[1,0,3,2] row_mask:0xf bank_mask:0xf bound_ctrl:1
	v_pk_fma_f32 v[54:55], v[52:53], v[8:9], v[10:11]
	v_add_f32_dpp v0, v0, v0 quad_perm:[2,3,0,1] row_mask:0xf bank_mask:0xf bound_ctrl:1
	s_nop 0
	s_nop 0
	v_add_f32_dpp v0, v0, v0 row_half_mirror row_mask:0xf bank_mask:0xf bound_ctrl:1
	s_nop 0
	s_nop 0
	v_add_f32_dpp v2, v0, v0 row_mirror row_mask:0xf bank_mask:0xf bound_ctrl:1
	v_add_f32_dpp v0, v0, v0 row_mirror row_mask:0xf bank_mask:0xf bound_ctrl:1
	s_nop 0
	s_waitcnt lgkmcnt(0)
	v_permlane16_swap_b32_e32 v0, v2
	v_add_f32_e32 v0, v0, v2
	v_pk_fma_f32 v[52:53], v[104:105], v[0:1], v[54:55] op_sel_hi:[1,0,1]
	v_pk_mul_f32 v[118:119], v[52:53], v[112:113] op_sel_hi:[0,1]
	v_pk_fma_f32 v[118:119], v[52:53], v[114:115], v[118:119] op_sel:[1,0,0]
	v_pk_mul_f32 v[98:99], v[110:111], v[98:99] op_sel:[1,0]
	s_nop 0
	v_add_f32_dpp v118, v118, v118 quad_perm:[1,0,3,2] row_mask:0xf bank_mask:0xf bound_ctrl:1
	v_add_f32_dpp v119, v119, v119 quad_perm:[1,0,3,2] row_mask:0xf bank_mask:0xf bound_ctrl:1
	v_pk_fma_f32 v[54:55], v[52:53], v[96:97], v[98:99]
	v_add_f32_dpp v118, v118, v118 quad_perm:[2,3,0,1] row_mask:0xf bank_mask:0xf bound_ctrl:1
	s_nop 0
	s_nop 0
	v_add_f32_dpp v118, v118, v118 row_half_mirror row_mask:0xf bank_mask:0xf bound_ctrl:1
	ds_write2_b32 v93, v1, v119 offset0:216 offset1:252
	ds_read_b128 v[4:7], v92
	ds_read_b128 v[8:11], v92 offset:16
	s_nop 0
	v_add_f32_dpp v2, v118, v118 row_mirror row_mask:0xf bank_mask:0xf bound_ctrl:1
	v_add_f32_dpp v118, v118, v118 row_mirror row_mask:0xf bank_mask:0xf bound_ctrl:1
	ds_read_b128 v[96:99], v92 offset:32
	ds_read_b128 v[100:103], v92 offset:48
	s_nop 0
	s_nop 0
	v_permlane16_swap_b32_e32 v118, v2
	v_add_f32_e32 v118, v118, v2
	v_pk_fma_f32 v[52:53], v[106:107], v[118:119], v[54:55] op_sel_hi:[1,0,1]
	s_branch .Lrw_yred

.Lrw_yred:
	s_min_u32 s83, s31, 32
	v_cmp_gt_u32_e32 vcc, s83, v87
	s_cmp_lg_u32 s88, 0
	s_cselect_b64 s[8:9], -1, 0
	v_cmp_ne_u32_e64 s[6:7], 0, v87
	s_or_b64 s[6:7], s[6:7], s[8:9]
	s_and_b64 s[8:9], vcc, s[6:7]
	v_lshl_add_u64 v[0:1], v[50:51], 0, s[88:89]
	v_lshl_add_u64 v[0:1], v[94:95], 0, v[0:1]
	v_add_co_u32_e32 v0, vcc, 0x10698000, v0
	s_nop 1
	v_addc_co_u32_e32 v1, vcc, 0, v1, vcc
	s_waitcnt lgkmcnt(0)
	v_add_f32_e32 v4, v4, v5
	v_add_f32_e32 v6, v6, v7
	v_add_f32_e32 v8, v8, v9
	v_add_f32_e32 v10, v10, v11
	v_add_f32_e32 v96, v96, v97
	v_add_f32_e32 v98, v98, v99
	v_add_f32_e32 v100, v100, v101
	v_add_f32_e32 v102, v102, v103
	v_add_f32_e32 v4, v4, v6
	v_add_f32_e32 v8, v8, v10
	v_add_f32_e32 v96, v96, v98
	v_add_f32_e32 v100, v100, v102
	v_add_f32_e32 v4, v4, v8
	v_add_f32_e32 v96, v96, v100
	v_add_f32_e32 v4, v4, v96
	s_and_saveexec_b64 s[6:7], s[8:9]
	global_store_dword v[0:1], v4, off
	s_branch .LBB0_681
